# adds: P8 sample-row modulation operands requested together (8 dependent load groups -> one) and attn_sample first 64-key group: 16 key quads requested together (loop unrolled)
# baseline (speedup 1.0000x reference)
; #define LAS __attribute__((address_space(3)))
; __device__ __forceinline__ void attn_sample_wave(const Frame& F, int unit) {
;     ...
;     const float sink = F.in[17][hq];
;     float sc[3][4];
; #pragma unroll
;     for (int kk = 0; kk < 3; ++kk) { const int kidx = kk * 64 + lane;
; #pragma unroll
;         for (int t = 0; t < 4; ++t) sc[kk][t] = 0.f;
;         if (kidx < 128) { const f32x4* kr = (const f32x4*)(F.in[2] + ((size_t)b * 128 + kidx) * 256 + g * 64);
; #pragma unroll 8
;             for (int d4 = 0; d4 < 16; ++d4) { const f32x4 kv = kr[d4];
; #pragma unroll
;                 for (int t = 0; t < 4; ++t) { const f32x4 q = *(const LAS f32x4*)(sq + t * 64 + d4 * 4); sc[kk][t] += kv[0] * q[0] + kv[1] * q[1] + kv[2] * q[2] + kv[3] * q[3]; } } }
.LBB0_509:
	s_lshl_b32 s28, s28, 2
	v_readlane_b32 s64, v245, 21
	v_mov_b32_e32 v0, s28
	v_readlane_b32 s66, v245, 23
	v_readlane_b32 s67, v245, 24
	s_and_b32 s28, s53, 12
	s_ashr_i32 s97, s96, 31
	s_ashr_i32 s95, s94, 31
	s_ashr_i32 s93, s92, 31
	s_ashr_i32 s83, s82, 31
	global_load_dword v61, v0, s[66:67]
	s_lshl_b32 s28, s28, 6
	s_add_u32 s34, s46, s28
	s_addc_u32 s35, s47, 0
	v_mov_b32_e32 v0, 0
	s_waitcnt vmcnt(1)
	v_lshl_add_u64 v[22:23], v[16:17], 0, s[34:35]
	s_mov_b64 vcc, 0
	s_mov_b32 s28, s90
	v_mov_b32_e32 v1, v0
	v_mov_b32_e32 v2, v0
	v_mov_b32_e32 v3, v0
	v_readlane_b32 s65, v245, 22
	v_readlane_b32 s68, v245, 25
	v_readlane_b32 s69, v245, 26
	v_readlane_b32 s70, v245, 27
	v_readlane_b32 s71, v245, 28
	v_readlane_b32 s72, v245, 29
	v_readlane_b32 s73, v245, 30
	v_readlane_b32 s74, v245, 31
	v_readlane_b32 s75, v245, 32
	v_readlane_b32 s76, v245, 33
	v_readlane_b32 s77, v245, 34
	v_readlane_b32 s78, v245, 35
	v_readlane_b32 s79, v245, 36
	global_load_dwordx4 v[100:103], v[22:23], off
	global_load_dwordx4 v[104:107], v[22:23], off offset:16
	global_load_dwordx4 v[108:111], v[22:23], off offset:32
	global_load_dwordx4 v[112:115], v[22:23], off offset:48
	global_load_dwordx4 v[116:119], v[22:23], off offset:64
	global_load_dwordx4 v[120:123], v[22:23], off offset:80
	global_load_dwordx4 v[124:127], v[22:23], off offset:96
	global_load_dwordx4 v[128:131], v[22:23], off offset:112
	global_load_dwordx4 v[162:165], v[22:23], off offset:128
	global_load_dwordx4 v[166:169], v[22:23], off offset:144
	global_load_dwordx4 v[170:173], v[22:23], off offset:160
	global_load_dwordx4 v[174:177], v[22:23], off offset:176
	global_load_dwordx4 v[178:181], v[22:23], off offset:192
	global_load_dwordx4 v[182:185], v[22:23], off offset:208
	global_load_dwordx4 v[186:189], v[22:23], off offset:224
	global_load_dwordx4 v[190:193], v[22:23], off offset:240
.LBB0_510:
	v_lshl_add_u64 v[82:83], v[22:23], 0, vcc
	s_waitcnt vmcnt(0)
	v_mov_b32_e32 v24, v112
	v_mov_b32_e32 v25, v113
	v_mov_b32_e32 v26, v114
	v_mov_b32_e32 v27, v115
	v_mov_b32_e32 v28, v108
	v_mov_b32_e32 v29, v109
	v_mov_b32_e32 v30, v110
	v_mov_b32_e32 v31, v111
	v_mov_b32_e32 v32, v104
	v_mov_b32_e32 v33, v105
	v_mov_b32_e32 v34, v106
	v_mov_b32_e32 v35, v107
	v_mov_b32_e32 v36, v100
	v_mov_b32_e32 v37, v101
	v_mov_b32_e32 v38, v102
	v_mov_b32_e32 v39, v103
	v_mov_b32_e32 v86, s28
	ds_read_b128 v[62:65], v86
	ds_read_b128 v[66:69], v86 offset:16
	ds_read_b128 v[70:73], v86 offset:32
	ds_read_b128 v[74:77], v86 offset:48
	ds_read_b128 v[78:81], v86 offset:256
	s_waitcnt lgkmcnt(4)
	v_mov_b32_e32 v85, v63
	s_addk_i32 s28, 0x80
	s_add_u32 vcc_lo, vcc_lo, 0x80
	s_addc_u32 vcc_hi, vcc_hi, 0
	s_waitcnt lgkmcnt(0)
	v_mov_b32_e32 v84, v78
	v_mov_b32_e32 v78, v79
	v_mov_b32_e32 v79, v62
	s_cmpk_lg_i32 vcc_lo, 0x100
	s_waitcnt vmcnt(0)
	v_pk_mul_f32 v[84:85], v[36:37], v[84:85]
	s_nop 0
	v_pk_fma_f32 v[62:63], v[36:37], v[78:79], v[84:85] op_sel:[1,0,0] op_sel_hi:[0,1,1]
	v_mov_b32_e32 v78, v80
	v_mov_b32_e32 v79, v64
	v_pk_fma_f32 v[62:63], v[38:39], v[78:79], v[62:63] op_sel_hi:[0,1,1]
	v_mov_b32_e32 v4, v39
	v_mov_b32_e32 v64, v81
	v_pk_fma_f32 v[62:63], v[4:5], v[64:65], v[62:63] op_sel_hi:[0,1,1]
	v_pk_add_f32 v[84:85], v[2:3], v[62:63]
	ds_read_b128 v[62:65], v86 offset:512
	ds_read_b128 v[78:81], v86 offset:768
	s_waitcnt lgkmcnt(1)
	v_mov_b32_e32 v3, v63
	s_waitcnt lgkmcnt(0)
	v_mov_b32_e32 v2, v78
	v_pk_mul_f32 v[2:3], v[36:37], v[2:3]
	v_mov_b32_e32 v78, v79
	v_mov_b32_e32 v79, v62
	v_pk_fma_f32 v[2:3], v[36:37], v[78:79], v[2:3] op_sel:[1,0,0] op_sel_hi:[0,1,1]
	v_mov_b32_e32 v36, v80
	v_mov_b32_e32 v37, v64
	v_pk_fma_f32 v[2:3], v[38:39], v[36:37], v[2:3] op_sel_hi:[0,1,1]
	v_mov_b32_e32 v64, v81
	v_pk_fma_f32 v[2:3], v[4:5], v[64:65], v[2:3] op_sel_hi:[0,1,1]
	v_pk_add_f32 v[62:63], v[0:1], v[2:3]
	ds_read_b128 v[0:3], v86 offset:272
	v_mov_b32_e32 v37, v67
	v_mov_b32_e32 v4, v35
	s_waitcnt lgkmcnt(0)
	v_mov_b32_e32 v36, v0
	v_pk_mul_f32 v[36:37], v[32:33], v[36:37]
	v_mov_b32_e32 v0, v1
	v_mov_b32_e32 v1, v66
	v_pk_fma_f32 v[0:1], v[32:33], v[0:1], v[36:37] op_sel:[1,0,0] op_sel_hi:[0,1,1]
	v_mov_b32_e32 v36, v2
	v_mov_b32_e32 v37, v68
	v_pk_fma_f32 v[0:1], v[34:35], v[36:37], v[0:1] op_sel_hi:[0,1,1]
	v_mov_b32_e32 v68, v3
	v_pk_fma_f32 v[0:1], v[4:5], v[68:69], v[0:1] op_sel_hi:[0,1,1]
	v_pk_add_f32 v[64:65], v[84:85], v[0:1]
	ds_read_b128 v[0:3], v86 offset:528
	ds_read_b128 v[36:39], v86 offset:784
	s_waitcnt lgkmcnt(1)
	v_mov_b32_e32 v67, v1
	s_waitcnt lgkmcnt(0)
	v_mov_b32_e32 v66, v36
	v_pk_mul_f32 v[66:67], v[32:33], v[66:67]
	v_mov_b32_e32 v36, v37
	v_mov_b32_e32 v37, v0
	v_pk_fma_f32 v[0:1], v[32:33], v[36:37], v[66:67] op_sel:[1,0,0] op_sel_hi:[0,1,1]
	v_mov_b32_e32 v32, v38
	v_mov_b32_e32 v33, v2
	v_pk_fma_f32 v[0:1], v[34:35], v[32:33], v[0:1] op_sel_hi:[0,1,1]
	v_mov_b32_e32 v2, v39
	v_pk_fma_f32 v[0:1], v[4:5], v[2:3], v[0:1] op_sel_hi:[0,1,1]
	v_pk_add_f32 v[36:37], v[62:63], v[0:1]
	ds_read_b128 v[0:3], v86 offset:288
	v_mov_b32_e32 v33, v71
	v_mov_b32_e32 v4, v31
	s_waitcnt lgkmcnt(0)
	v_mov_b32_e32 v32, v0
	v_pk_mul_f32 v[32:33], v[28:29], v[32:33]
	v_mov_b32_e32 v0, v1
	v_mov_b32_e32 v1, v70
	v_pk_fma_f32 v[0:1], v[28:29], v[0:1], v[32:33] op_sel:[1,0,0] op_sel_hi:[0,1,1]
	v_mov_b32_e32 v32, v2
	v_mov_b32_e32 v33, v72
	v_pk_fma_f32 v[0:1], v[30:31], v[32:33], v[0:1] op_sel_hi:[0,1,1]
	v_mov_b32_e32 v72, v3
	v_pk_fma_f32 v[0:1], v[4:5], v[72:73], v[0:1] op_sel_hi:[0,1,1]
	v_pk_add_f32 v[38:39], v[64:65], v[0:1]
	ds_read_b128 v[0:3], v86 offset:544
	ds_read_b128 v[32:35], v86 offset:800
	s_waitcnt lgkmcnt(1)
	v_mov_b32_e32 v63, v1
	s_waitcnt lgkmcnt(0)
; #define LAS __attribute__((address_space(3)))
; __device__ __forceinline__ void attn_sample_wave(const Frame& F, int unit) {
;     ...
;         if (kidx < 128) { const f32x4* kr = (const f32x4*)(F.in[2] + ((size_t)b * 128 + kidx) * 256 + g * 64);
; #pragma unroll 8
;             for (int d4 = 0; d4 < 16; ++d4) { const f32x4 kv = kr[d4];
; #pragma unroll
;                 for (int t = 0; t < 4; ++t) { const f32x4 q = *(const LAS f32x4*)(sq + t * 64 + d4 * 4); sc[kk][t] += kv[0] * q[0] + kv[1] * q[1] + kv[2] * q[2] + kv[3] * q[3]; } } }
	v_mov_b32_e32 v62, v32
	v_pk_mul_f32 v[62:63], v[28:29], v[62:63]
	v_mov_b32_e32 v32, v33
	v_mov_b32_e32 v33, v0
	v_pk_fma_f32 v[0:1], v[28:29], v[32:33], v[62:63] op_sel:[1,0,0] op_sel_hi:[0,1,1]
	v_mov_b32_e32 v28, v34
	v_mov_b32_e32 v29, v2
	v_pk_fma_f32 v[0:1], v[30:31], v[28:29], v[0:1] op_sel_hi:[0,1,1]
	v_mov_b32_e32 v2, v35
	v_pk_fma_f32 v[0:1], v[4:5], v[2:3], v[0:1] op_sel_hi:[0,1,1]
	v_pk_add_f32 v[32:33], v[36:37], v[0:1]
	ds_read_b128 v[0:3], v86 offset:304
	v_mov_b32_e32 v29, v75
	v_mov_b32_e32 v4, v27
	s_waitcnt lgkmcnt(0)
	v_mov_b32_e32 v28, v0
	v_pk_mul_f32 v[28:29], v[24:25], v[28:29]
	v_mov_b32_e32 v0, v1
	v_mov_b32_e32 v1, v74
	v_pk_fma_f32 v[0:1], v[24:25], v[0:1], v[28:29] op_sel:[1,0,0] op_sel_hi:[0,1,1]
	v_mov_b32_e32 v28, v2
	v_mov_b32_e32 v29, v76
	v_pk_fma_f32 v[0:1], v[26:27], v[28:29], v[0:1] op_sel_hi:[0,1,1]
	v_mov_b32_e32 v76, v3
	v_pk_fma_f32 v[0:1], v[4:5], v[76:77], v[0:1] op_sel_hi:[0,1,1]
	v_pk_add_f32 v[66:67], v[38:39], v[0:1]
	ds_read_b128 v[0:3], v86 offset:560
	ds_read_b128 v[28:31], v86 offset:816
	s_waitcnt lgkmcnt(1)
	v_mov_b32_e32 v35, v1
	s_waitcnt lgkmcnt(0)
	v_mov_b32_e32 v34, v28
	v_pk_mul_f32 v[34:35], v[24:25], v[34:35]
	v_mov_b32_e32 v28, v29
	v_mov_b32_e32 v29, v0
	v_pk_fma_f32 v[0:1], v[24:25], v[28:29], v[34:35] op_sel:[1,0,0] op_sel_hi:[0,1,1]
	v_mov_b32_e32 v24, v30
	v_mov_b32_e32 v25, v2
	v_pk_fma_f32 v[0:1], v[26:27], v[24:25], v[0:1] op_sel_hi:[0,1,1]
	v_mov_b32_e32 v2, v31
	v_pk_fma_f32 v[0:1], v[4:5], v[2:3], v[0:1] op_sel_hi:[0,1,1]
	v_pk_add_f32 v[68:69], v[32:33], v[0:1]
	v_mov_b32_e32 v24, v128
	v_mov_b32_e32 v25, v129
	v_mov_b32_e32 v26, v130
	v_mov_b32_e32 v27, v131
	v_mov_b32_e32 v0, v124
	v_mov_b32_e32 v1, v125
	v_mov_b32_e32 v2, v126
	v_mov_b32_e32 v3, v127
	v_mov_b32_e32 v28, v120
	v_mov_b32_e32 v29, v121
	v_mov_b32_e32 v30, v122
	v_mov_b32_e32 v31, v123
	v_mov_b32_e32 v32, v116
	v_mov_b32_e32 v33, v117
	v_mov_b32_e32 v34, v118
	v_mov_b32_e32 v35, v119
	ds_read_b128 v[36:39], v86 offset:64
	ds_read_b128 v[62:65], v86 offset:320
	s_waitcnt lgkmcnt(1)
	v_mov_b32_e32 v71, v37
	s_waitcnt lgkmcnt(0)
	v_mov_b32_e32 v70, v62
	v_mov_b32_e32 v62, v63
	v_mov_b32_e32 v63, v36
	s_waitcnt vmcnt(0)
	v_pk_mul_f32 v[70:71], v[32:33], v[70:71]
	s_nop 0
	v_pk_fma_f32 v[36:37], v[32:33], v[62:63], v[70:71] op_sel:[1,0,0] op_sel_hi:[0,1,1]
	v_mov_b32_e32 v62, v64
	v_mov_b32_e32 v63, v38
	v_pk_fma_f32 v[36:37], v[34:35], v[62:63], v[36:37] op_sel_hi:[0,1,1]
	v_mov_b32_e32 v4, v35
	v_mov_b32_e32 v38, v65
	v_pk_fma_f32 v[36:37], v[4:5], v[38:39], v[36:37] op_sel_hi:[0,1,1]
	v_pk_add_f32 v[66:67], v[66:67], v[36:37]
	ds_read_b128 v[36:39], v86 offset:576
	ds_read_b128 v[62:65], v86 offset:832
	s_waitcnt lgkmcnt(1)
	v_mov_b32_e32 v71, v37
	s_waitcnt lgkmcnt(0)
	v_mov_b32_e32 v70, v62
	v_pk_mul_f32 v[70:71], v[32:33], v[70:71]
	v_mov_b32_e32 v62, v63
	v_mov_b32_e32 v63, v36
	v_pk_fma_f32 v[32:33], v[32:33], v[62:63], v[70:71] op_sel:[1,0,0] op_sel_hi:[0,1,1]
	v_mov_b32_e32 v36, v64
	v_mov_b32_e32 v37, v38
	v_pk_fma_f32 v[32:33], v[34:35], v[36:37], v[32:33] op_sel_hi:[0,1,1]
	v_mov_b32_e32 v38, v65
	v_pk_fma_f32 v[32:33], v[4:5], v[38:39], v[32:33] op_sel_hi:[0,1,1]
	v_pk_add_f32 v[62:63], v[68:69], v[32:33]
	ds_read_b128 v[32:35], v86 offset:80
	ds_read_b128 v[36:39], v86 offset:336
	v_mov_b32_e32 v4, v31
	s_waitcnt lgkmcnt(1)
	v_mov_b32_e32 v65, v33
	s_waitcnt lgkmcnt(0)
	v_mov_b32_e32 v64, v36
	v_pk_mul_f32 v[64:65], v[28:29], v[64:65]
	v_mov_b32_e32 v36, v37
	v_mov_b32_e32 v37, v32
	v_pk_fma_f32 v[32:33], v[28:29], v[36:37], v[64:65] op_sel:[1,0,0] op_sel_hi:[0,1,1]
	v_mov_b32_e32 v36, v38
	v_mov_b32_e32 v37, v34
	v_pk_fma_f32 v[32:33], v[30:31], v[36:37], v[32:33] op_sel_hi:[0,1,1]
	v_mov_b32_e32 v34, v39
	v_pk_fma_f32 v[32:33], v[4:5], v[34:35], v[32:33] op_sel_hi:[0,1,1]
	v_pk_add_f32 v[64:65], v[66:67], v[32:33]
	ds_read_b128 v[32:35], v86 offset:592
	ds_read_b128 v[36:39], v86 offset:848
	s_waitcnt lgkmcnt(1)
	v_mov_b32_e32 v67, v33
	s_waitcnt lgkmcnt(0)
	v_mov_b32_e32 v66, v36
	v_pk_mul_f32 v[66:67], v[28:29], v[66:67]
	v_mov_b32_e32 v36, v37
	v_mov_b32_e32 v37, v32
	v_pk_fma_f32 v[28:29], v[28:29], v[36:37], v[66:67] op_sel:[1,0,0] op_sel_hi:[0,1,1]
	v_mov_b32_e32 v32, v38
	v_mov_b32_e32 v33, v34
	v_pk_fma_f32 v[28:29], v[30:31], v[32:33], v[28:29] op_sel_hi:[0,1,1]
	v_mov_b32_e32 v34, v39
	v_pk_fma_f32 v[28:29], v[4:5], v[34:35], v[28:29] op_sel_hi:[0,1,1]
	v_pk_add_f32 v[36:37], v[62:63], v[28:29]
	ds_read_b128 v[28:31], v86 offset:96
	ds_read_b128 v[32:35], v86 offset:352
	v_mov_b32_e32 v4, v3
	s_waitcnt lgkmcnt(1)
	v_mov_b32_e32 v39, v29
	s_waitcnt lgkmcnt(0)
	v_mov_b32_e32 v38, v32
	v_pk_mul_f32 v[38:39], v[0:1], v[38:39]
	v_mov_b32_e32 v32, v33
	v_mov_b32_e32 v33, v28
	v_pk_fma_f32 v[28:29], v[0:1], v[32:33], v[38:39] op_sel:[1,0,0] op_sel_hi:[0,1,1]
	v_mov_b32_e32 v32, v34
	v_mov_b32_e32 v33, v30
	v_pk_fma_f32 v[28:29], v[2:3], v[32:33], v[28:29] op_sel_hi:[0,1,1]
	v_mov_b32_e32 v30, v35
	v_pk_fma_f32 v[28:29], v[4:5], v[30:31], v[28:29] op_sel_hi:[0,1,1]
	v_pk_add_f32 v[38:39], v[64:65], v[28:29]
	ds_read_b128 v[28:31], v86 offset:608
	ds_read_b128 v[32:35], v86 offset:864
	s_waitcnt lgkmcnt(1)
	v_mov_b32_e32 v63, v29
	s_waitcnt lgkmcnt(0)
	v_mov_b32_e32 v62, v32
	v_pk_mul_f32 v[62:63], v[0:1], v[62:63]
	v_mov_b32_e32 v32, v33
	v_mov_b32_e32 v33, v28
	v_pk_fma_f32 v[0:1], v[0:1], v[32:33], v[62:63] op_sel:[1,0,0] op_sel_hi:[0,1,1]
	v_mov_b32_e32 v28, v34
	v_mov_b32_e32 v29, v30
	v_pk_fma_f32 v[0:1], v[2:3], v[28:29], v[0:1] op_sel_hi:[0,1,1]
	v_mov_b32_e32 v30, v35
	v_pk_fma_f32 v[0:1], v[4:5], v[30:31], v[0:1] op_sel_hi:[0,1,1]
	v_pk_add_f32 v[36:37], v[36:37], v[0:1]
	ds_read_b128 v[0:3], v86 offset:112
	ds_read_b128 v[28:31], v86 offset:368
	v_mov_b32_e32 v4, v27
	s_waitcnt lgkmcnt(1)
; #define LAS __attribute__((address_space(3)))
; __device__ __forceinline__ void attn_sample_wave(const Frame& F, int unit) {
;     ...
;         if (kidx < 128) { const f32x4* kr = (const f32x4*)(F.in[2] + ((size_t)b * 128 + kidx) * 256 + g * 64);
; #pragma unroll 8
;             for (int d4 = 0; d4 < 16; ++d4) { const f32x4 kv = kr[d4];
; #pragma unroll
;                 for (int t = 0; t < 4; ++t) { const f32x4 q = *(const LAS f32x4*)(sq + t * 64 + d4 * 4); sc[kk][t] += kv[0] * q[0] + kv[1] * q[1] + kv[2] * q[2] + kv[3] * q[3]; } } }
	v_mov_b32_e32 v33, v1
	s_waitcnt lgkmcnt(0)
	v_mov_b32_e32 v32, v28
	v_pk_mul_f32 v[32:33], v[24:25], v[32:33]
	v_mov_b32_e32 v28, v29
	v_mov_b32_e32 v29, v0
	v_pk_fma_f32 v[0:1], v[24:25], v[28:29], v[32:33] op_sel:[1,0,0] op_sel_hi:[0,1,1]
	v_mov_b32_e32 v28, v30
	v_mov_b32_e32 v29, v2
	v_pk_fma_f32 v[0:1], v[26:27], v[28:29], v[0:1] op_sel_hi:[0,1,1]
	v_mov_b32_e32 v2, v31
	ds_read_b128 v[28:31], v86 offset:624
	ds_read_b128 v[32:35], v86 offset:880
	v_pk_fma_f32 v[0:1], v[4:5], v[2:3], v[0:1] op_sel_hi:[0,1,1]
	v_pk_add_f32 v[2:3], v[38:39], v[0:1]
	s_waitcnt lgkmcnt(1)
	v_mov_b32_e32 v1, v29
	s_waitcnt lgkmcnt(0)
	v_mov_b32_e32 v0, v32
	v_pk_mul_f32 v[0:1], v[24:25], v[0:1]
	v_mov_b32_e32 v32, v33
	v_mov_b32_e32 v33, v28
	v_pk_fma_f32 v[0:1], v[24:25], v[32:33], v[0:1] op_sel:[1,0,0] op_sel_hi:[0,1,1]
	v_mov_b32_e32 v24, v34
	v_mov_b32_e32 v25, v30
	v_pk_fma_f32 v[0:1], v[26:27], v[24:25], v[0:1] op_sel_hi:[0,1,1]
	v_mov_b32_e32 v30, v35
	v_pk_fma_f32 v[0:1], v[4:5], v[30:31], v[0:1] op_sel_hi:[0,1,1]
	v_pk_add_f32 v[0:1], v[36:37], v[0:1]
	v_lshl_add_u64 v[82:83], v[22:23], 0, vcc
	v_mov_b32_e32 v24, v174
	v_mov_b32_e32 v25, v175
	v_mov_b32_e32 v26, v176
	v_mov_b32_e32 v27, v177
	v_mov_b32_e32 v28, v170
	v_mov_b32_e32 v29, v171
	v_mov_b32_e32 v30, v172
	v_mov_b32_e32 v31, v173
	v_mov_b32_e32 v32, v166
	v_mov_b32_e32 v33, v167
	v_mov_b32_e32 v34, v168
	v_mov_b32_e32 v35, v169
	v_mov_b32_e32 v36, v162
	v_mov_b32_e32 v37, v163
	v_mov_b32_e32 v38, v164
	v_mov_b32_e32 v39, v165
	v_mov_b32_e32 v86, s28
	ds_read_b128 v[62:65], v86
	ds_read_b128 v[66:69], v86 offset:16
	ds_read_b128 v[70:73], v86 offset:32
	ds_read_b128 v[74:77], v86 offset:48
	ds_read_b128 v[78:81], v86 offset:256
	s_waitcnt lgkmcnt(4)
	v_mov_b32_e32 v85, v63
	s_addk_i32 s28, 0x80
	s_add_u32 vcc_lo, vcc_lo, 0x80
	s_addc_u32 vcc_hi, vcc_hi, 0
	s_waitcnt lgkmcnt(0)
	v_mov_b32_e32 v84, v78
	v_mov_b32_e32 v78, v79
	v_mov_b32_e32 v79, v62
	s_cmpk_lg_i32 vcc_lo, 0x100
	s_waitcnt vmcnt(0)
	v_pk_mul_f32 v[84:85], v[36:37], v[84:85]
	s_nop 0
	v_pk_fma_f32 v[62:63], v[36:37], v[78:79], v[84:85] op_sel:[1,0,0] op_sel_hi:[0,1,1]
	v_mov_b32_e32 v78, v80
	v_mov_b32_e32 v79, v64
	v_pk_fma_f32 v[62:63], v[38:39], v[78:79], v[62:63] op_sel_hi:[0,1,1]
	v_mov_b32_e32 v4, v39
	v_mov_b32_e32 v64, v81
	v_pk_fma_f32 v[62:63], v[4:5], v[64:65], v[62:63] op_sel_hi:[0,1,1]
	v_pk_add_f32 v[84:85], v[2:3], v[62:63]
	ds_read_b128 v[62:65], v86 offset:512
	ds_read_b128 v[78:81], v86 offset:768
	s_waitcnt lgkmcnt(1)
	v_mov_b32_e32 v3, v63
	s_waitcnt lgkmcnt(0)
	v_mov_b32_e32 v2, v78
	v_pk_mul_f32 v[2:3], v[36:37], v[2:3]
	v_mov_b32_e32 v78, v79
	v_mov_b32_e32 v79, v62
	v_pk_fma_f32 v[2:3], v[36:37], v[78:79], v[2:3] op_sel:[1,0,0] op_sel_hi:[0,1,1]
	v_mov_b32_e32 v36, v80
	v_mov_b32_e32 v37, v64
	v_pk_fma_f32 v[2:3], v[38:39], v[36:37], v[2:3] op_sel_hi:[0,1,1]
	v_mov_b32_e32 v64, v81
	v_pk_fma_f32 v[2:3], v[4:5], v[64:65], v[2:3] op_sel_hi:[0,1,1]
	v_pk_add_f32 v[62:63], v[0:1], v[2:3]
	ds_read_b128 v[0:3], v86 offset:272
	v_mov_b32_e32 v37, v67
	v_mov_b32_e32 v4, v35
	s_waitcnt lgkmcnt(0)
	v_mov_b32_e32 v36, v0
	v_pk_mul_f32 v[36:37], v[32:33], v[36:37]
	v_mov_b32_e32 v0, v1
	v_mov_b32_e32 v1, v66
	v_pk_fma_f32 v[0:1], v[32:33], v[0:1], v[36:37] op_sel:[1,0,0] op_sel_hi:[0,1,1]
	v_mov_b32_e32 v36, v2
	v_mov_b32_e32 v37, v68
	v_pk_fma_f32 v[0:1], v[34:35], v[36:37], v[0:1] op_sel_hi:[0,1,1]
	v_mov_b32_e32 v68, v3
	v_pk_fma_f32 v[0:1], v[4:5], v[68:69], v[0:1] op_sel_hi:[0,1,1]
	v_pk_add_f32 v[64:65], v[84:85], v[0:1]
	ds_read_b128 v[0:3], v86 offset:528
	ds_read_b128 v[36:39], v86 offset:784
	s_waitcnt lgkmcnt(1)
	v_mov_b32_e32 v67, v1
	s_waitcnt lgkmcnt(0)
	v_mov_b32_e32 v66, v36
	v_pk_mul_f32 v[66:67], v[32:33], v[66:67]
	v_mov_b32_e32 v36, v37
	v_mov_b32_e32 v37, v0
	v_pk_fma_f32 v[0:1], v[32:33], v[36:37], v[66:67] op_sel:[1,0,0] op_sel_hi:[0,1,1]
	v_mov_b32_e32 v32, v38
	v_mov_b32_e32 v33, v2
	v_pk_fma_f32 v[0:1], v[34:35], v[32:33], v[0:1] op_sel_hi:[0,1,1]
	v_mov_b32_e32 v2, v39
	v_pk_fma_f32 v[0:1], v[4:5], v[2:3], v[0:1] op_sel_hi:[0,1,1]
	v_pk_add_f32 v[36:37], v[62:63], v[0:1]
	ds_read_b128 v[0:3], v86 offset:288
	v_mov_b32_e32 v33, v71
	v_mov_b32_e32 v4, v31
	s_waitcnt lgkmcnt(0)
	v_mov_b32_e32 v32, v0
	v_pk_mul_f32 v[32:33], v[28:29], v[32:33]
	v_mov_b32_e32 v0, v1
	v_mov_b32_e32 v1, v70
	v_pk_fma_f32 v[0:1], v[28:29], v[0:1], v[32:33] op_sel:[1,0,0] op_sel_hi:[0,1,1]
	v_mov_b32_e32 v32, v2
	v_mov_b32_e32 v33, v72
	v_pk_fma_f32 v[0:1], v[30:31], v[32:33], v[0:1] op_sel_hi:[0,1,1]
	v_mov_b32_e32 v72, v3
	v_pk_fma_f32 v[0:1], v[4:5], v[72:73], v[0:1] op_sel_hi:[0,1,1]
	v_pk_add_f32 v[38:39], v[64:65], v[0:1]
	ds_read_b128 v[0:3], v86 offset:544
	ds_read_b128 v[32:35], v86 offset:800
	s_waitcnt lgkmcnt(1)
	v_mov_b32_e32 v63, v1
	s_waitcnt lgkmcnt(0)
	v_mov_b32_e32 v62, v32
	v_pk_mul_f32 v[62:63], v[28:29], v[62:63]
	v_mov_b32_e32 v32, v33
	v_mov_b32_e32 v33, v0
	v_pk_fma_f32 v[0:1], v[28:29], v[32:33], v[62:63] op_sel:[1,0,0] op_sel_hi:[0,1,1]
	v_mov_b32_e32 v28, v34
	v_mov_b32_e32 v29, v2
	v_pk_fma_f32 v[0:1], v[30:31], v[28:29], v[0:1] op_sel_hi:[0,1,1]
	v_mov_b32_e32 v2, v35
	v_pk_fma_f32 v[0:1], v[4:5], v[2:3], v[0:1] op_sel_hi:[0,1,1]
	v_pk_add_f32 v[32:33], v[36:37], v[0:1]
	ds_read_b128 v[0:3], v86 offset:304
	v_mov_b32_e32 v29, v75
	v_mov_b32_e32 v4, v27
	s_waitcnt lgkmcnt(0)
	v_mov_b32_e32 v28, v0
	v_pk_mul_f32 v[28:29], v[24:25], v[28:29]
	v_mov_b32_e32 v0, v1
	v_mov_b32_e32 v1, v74
	v_pk_fma_f32 v[0:1], v[24:25], v[0:1], v[28:29] op_sel:[1,0,0] op_sel_hi:[0,1,1]
	v_mov_b32_e32 v28, v2
	v_mov_b32_e32 v29, v76
	v_pk_fma_f32 v[0:1], v[26:27], v[28:29], v[0:1] op_sel_hi:[0,1,1]
	v_mov_b32_e32 v76, v3
	v_pk_fma_f32 v[0:1], v[4:5], v[76:77], v[0:1] op_sel_hi:[0,1,1]
	v_pk_add_f32 v[66:67], v[38:39], v[0:1]
	ds_read_b128 v[0:3], v86 offset:560
	ds_read_b128 v[28:31], v86 offset:816
	s_waitcnt lgkmcnt(1)
; #define LAS __attribute__((address_space(3)))
; __device__ __forceinline__ void attn_sample_wave(const Frame& F, int unit) {
;     ...
;     for (int kk = 0; kk < 3; ++kk) { const int kidx = kk * 64 + lane;
; #pragma unroll
;         for (int t = 0; t < 4; ++t) sc[kk][t] = 0.f;
;         if (kidx < 128) { const f32x4* kr = (const f32x4*)(F.in[2] + ((size_t)b * 128 + kidx) * 256 + g * 64);
; #pragma unroll 8
;             for (int d4 = 0; d4 < 16; ++d4) { const f32x4 kv = kr[d4];
; #pragma unroll
;                 for (int t = 0; t < 4; ++t) { const f32x4 q = *(const LAS f32x4*)(sq + t * 64 + d4 * 4); sc[kk][t] += kv[0] * q[0] + kv[1] * q[1] + kv[2] * q[2] + kv[3] * q[3]; } } }
	v_mov_b32_e32 v35, v1
	s_waitcnt lgkmcnt(0)
	v_mov_b32_e32 v34, v28
	v_pk_mul_f32 v[34:35], v[24:25], v[34:35]
	v_mov_b32_e32 v28, v29
	v_mov_b32_e32 v29, v0
	v_pk_fma_f32 v[0:1], v[24:25], v[28:29], v[34:35] op_sel:[1,0,0] op_sel_hi:[0,1,1]
	v_mov_b32_e32 v24, v30
	v_mov_b32_e32 v25, v2
	v_pk_fma_f32 v[0:1], v[26:27], v[24:25], v[0:1] op_sel_hi:[0,1,1]
	v_mov_b32_e32 v2, v31
	v_pk_fma_f32 v[0:1], v[4:5], v[2:3], v[0:1] op_sel_hi:[0,1,1]
	v_pk_add_f32 v[68:69], v[32:33], v[0:1]
	v_mov_b32_e32 v24, v190
	v_mov_b32_e32 v25, v191
	v_mov_b32_e32 v26, v192
	v_mov_b32_e32 v27, v193
	v_mov_b32_e32 v0, v186
	v_mov_b32_e32 v1, v187
	v_mov_b32_e32 v2, v188
	v_mov_b32_e32 v3, v189
	v_mov_b32_e32 v28, v182
	v_mov_b32_e32 v29, v183
	v_mov_b32_e32 v30, v184
	v_mov_b32_e32 v31, v185
	v_mov_b32_e32 v32, v178
	v_mov_b32_e32 v33, v179
	v_mov_b32_e32 v34, v180
	v_mov_b32_e32 v35, v181
	ds_read_b128 v[36:39], v86 offset:64
	ds_read_b128 v[62:65], v86 offset:320
	s_waitcnt lgkmcnt(1)
	v_mov_b32_e32 v71, v37
	s_waitcnt lgkmcnt(0)
	v_mov_b32_e32 v70, v62
	v_mov_b32_e32 v62, v63
	v_mov_b32_e32 v63, v36
	s_waitcnt vmcnt(0)
	v_pk_mul_f32 v[70:71], v[32:33], v[70:71]
	s_nop 0
	v_pk_fma_f32 v[36:37], v[32:33], v[62:63], v[70:71] op_sel:[1,0,0] op_sel_hi:[0,1,1]
	v_mov_b32_e32 v62, v64
	v_mov_b32_e32 v63, v38
	v_pk_fma_f32 v[36:37], v[34:35], v[62:63], v[36:37] op_sel_hi:[0,1,1]
	v_mov_b32_e32 v4, v35
	v_mov_b32_e32 v38, v65
	v_pk_fma_f32 v[36:37], v[4:5], v[38:39], v[36:37] op_sel_hi:[0,1,1]
	v_pk_add_f32 v[66:67], v[66:67], v[36:37]
	ds_read_b128 v[36:39], v86 offset:576
	ds_read_b128 v[62:65], v86 offset:832
	s_waitcnt lgkmcnt(1)
	v_mov_b32_e32 v71, v37
	s_waitcnt lgkmcnt(0)
	v_mov_b32_e32 v70, v62
	v_pk_mul_f32 v[70:71], v[32:33], v[70:71]
	v_mov_b32_e32 v62, v63
	v_mov_b32_e32 v63, v36
	v_pk_fma_f32 v[32:33], v[32:33], v[62:63], v[70:71] op_sel:[1,0,0] op_sel_hi:[0,1,1]
	v_mov_b32_e32 v36, v64
	v_mov_b32_e32 v37, v38
	v_pk_fma_f32 v[32:33], v[34:35], v[36:37], v[32:33] op_sel_hi:[0,1,1]
	v_mov_b32_e32 v38, v65
	v_pk_fma_f32 v[32:33], v[4:5], v[38:39], v[32:33] op_sel_hi:[0,1,1]
	v_pk_add_f32 v[62:63], v[68:69], v[32:33]
	ds_read_b128 v[32:35], v86 offset:80
	ds_read_b128 v[36:39], v86 offset:336
	v_mov_b32_e32 v4, v31
	s_waitcnt lgkmcnt(1)
	v_mov_b32_e32 v65, v33
	s_waitcnt lgkmcnt(0)
	v_mov_b32_e32 v64, v36
	v_pk_mul_f32 v[64:65], v[28:29], v[64:65]
	v_mov_b32_e32 v36, v37
	v_mov_b32_e32 v37, v32
	v_pk_fma_f32 v[32:33], v[28:29], v[36:37], v[64:65] op_sel:[1,0,0] op_sel_hi:[0,1,1]
	v_mov_b32_e32 v36, v38
	v_mov_b32_e32 v37, v34
	v_pk_fma_f32 v[32:33], v[30:31], v[36:37], v[32:33] op_sel_hi:[0,1,1]
	v_mov_b32_e32 v34, v39
	v_pk_fma_f32 v[32:33], v[4:5], v[34:35], v[32:33] op_sel_hi:[0,1,1]
	v_pk_add_f32 v[64:65], v[66:67], v[32:33]
	ds_read_b128 v[32:35], v86 offset:592
	ds_read_b128 v[36:39], v86 offset:848
	s_waitcnt lgkmcnt(1)
	v_mov_b32_e32 v67, v33
	s_waitcnt lgkmcnt(0)
	v_mov_b32_e32 v66, v36
	v_pk_mul_f32 v[66:67], v[28:29], v[66:67]
	v_mov_b32_e32 v36, v37
	v_mov_b32_e32 v37, v32
	v_pk_fma_f32 v[28:29], v[28:29], v[36:37], v[66:67] op_sel:[1,0,0] op_sel_hi:[0,1,1]
	v_mov_b32_e32 v32, v38
	v_mov_b32_e32 v33, v34
	v_pk_fma_f32 v[28:29], v[30:31], v[32:33], v[28:29] op_sel_hi:[0,1,1]
	v_mov_b32_e32 v34, v39
	v_pk_fma_f32 v[28:29], v[4:5], v[34:35], v[28:29] op_sel_hi:[0,1,1]
	v_pk_add_f32 v[36:37], v[62:63], v[28:29]
	ds_read_b128 v[28:31], v86 offset:96
	ds_read_b128 v[32:35], v86 offset:352
	v_mov_b32_e32 v4, v3
	s_waitcnt lgkmcnt(1)
	v_mov_b32_e32 v39, v29
	s_waitcnt lgkmcnt(0)
	v_mov_b32_e32 v38, v32
	v_pk_mul_f32 v[38:39], v[0:1], v[38:39]
	v_mov_b32_e32 v32, v33
	v_mov_b32_e32 v33, v28
	v_pk_fma_f32 v[28:29], v[0:1], v[32:33], v[38:39] op_sel:[1,0,0] op_sel_hi:[0,1,1]
	v_mov_b32_e32 v32, v34
	v_mov_b32_e32 v33, v30
	v_pk_fma_f32 v[28:29], v[2:3], v[32:33], v[28:29] op_sel_hi:[0,1,1]
	v_mov_b32_e32 v30, v35
	v_pk_fma_f32 v[28:29], v[4:5], v[30:31], v[28:29] op_sel_hi:[0,1,1]
	v_pk_add_f32 v[38:39], v[64:65], v[28:29]
	ds_read_b128 v[28:31], v86 offset:608
	ds_read_b128 v[32:35], v86 offset:864
	s_waitcnt lgkmcnt(1)
	v_mov_b32_e32 v63, v29
	s_waitcnt lgkmcnt(0)
	v_mov_b32_e32 v62, v32
	v_pk_mul_f32 v[62:63], v[0:1], v[62:63]
	v_mov_b32_e32 v32, v33
	v_mov_b32_e32 v33, v28
	v_pk_fma_f32 v[0:1], v[0:1], v[32:33], v[62:63] op_sel:[1,0,0] op_sel_hi:[0,1,1]
	v_mov_b32_e32 v28, v34
	v_mov_b32_e32 v29, v30
	v_pk_fma_f32 v[0:1], v[2:3], v[28:29], v[0:1] op_sel_hi:[0,1,1]
	v_mov_b32_e32 v30, v35
	v_pk_fma_f32 v[0:1], v[4:5], v[30:31], v[0:1] op_sel_hi:[0,1,1]
	v_pk_add_f32 v[36:37], v[36:37], v[0:1]
	ds_read_b128 v[0:3], v86 offset:112
	ds_read_b128 v[28:31], v86 offset:368
	v_mov_b32_e32 v4, v27
	s_waitcnt lgkmcnt(1)
	v_mov_b32_e32 v33, v1
	s_waitcnt lgkmcnt(0)
	v_mov_b32_e32 v32, v28
	v_pk_mul_f32 v[32:33], v[24:25], v[32:33]
	v_mov_b32_e32 v28, v29
	v_mov_b32_e32 v29, v0
	v_pk_fma_f32 v[0:1], v[24:25], v[28:29], v[32:33] op_sel:[1,0,0] op_sel_hi:[0,1,1]
	v_mov_b32_e32 v28, v30
	v_mov_b32_e32 v29, v2
	v_pk_fma_f32 v[0:1], v[26:27], v[28:29], v[0:1] op_sel_hi:[0,1,1]
	v_mov_b32_e32 v2, v31
	ds_read_b128 v[28:31], v86 offset:624
	ds_read_b128 v[32:35], v86 offset:880
	v_pk_fma_f32 v[0:1], v[4:5], v[2:3], v[0:1] op_sel_hi:[0,1,1]
	v_pk_add_f32 v[2:3], v[38:39], v[0:1]
	s_waitcnt lgkmcnt(1)
	v_mov_b32_e32 v1, v29
	s_waitcnt lgkmcnt(0)
	v_mov_b32_e32 v0, v32
	v_pk_mul_f32 v[0:1], v[24:25], v[0:1]
	v_mov_b32_e32 v32, v33
	v_mov_b32_e32 v33, v28
	v_pk_fma_f32 v[0:1], v[24:25], v[32:33], v[0:1] op_sel:[1,0,0] op_sel_hi:[0,1,1]
	v_mov_b32_e32 v24, v34
	v_mov_b32_e32 v25, v30
	v_pk_fma_f32 v[0:1], v[26:27], v[24:25], v[0:1] op_sel_hi:[0,1,1]
	v_mov_b32_e32 v30, v35
	v_pk_fma_f32 v[0:1], v[4:5], v[30:31], v[0:1] op_sel_hi:[0,1,1]
	v_pk_add_f32 v[0:1], v[36:37], v[0:1]
	v_mov_b32_e32 v22, 0
	v_lshl_add_u64 v[24:25], v[18:19], 0, s[34:35]
	s_mov_b32 s28, 0
	v_mov_b32_e32 v23, v22
	v_mov_b32_e32 v26, v22
	v_mov_b32_e32 v27, v22

; template <bool GATES>
; __device__ __forceinline__ void norm_mod_phase(const Frame& F, const float* src0, const float* src1, const float* nw, int sh_off, int sc_off, int nparts, float* x1out) {
;     ...
;         const float* xr = r < SP ? src0 + (size_t)r * D : src1 + (size_t)(r - SP) * D;
;         f32x4 xv[8]; float ss = 0.f;
; #pragma unroll
;         for (int i = 0; i < 8; ++i) xv[i] = ((const f32x4*)xr)[i * 64 + F.lane];
;         if (r >= SP) { const float* mr = mod + (size_t)((r - SP) >> 2) * NMOD;
; #pragma unroll
;             for (int i = 0; i < 8; ++i) { const int c4 = i * 64 + F.lane; const f32x4 w = ((const f32x4*)nw)[c4], sc = ((const f32x4*)(mr + sc_off))[c4]; shv[i] = ((const f32x4*)(mr + sh_off))[c4]; av[i] = w * (sc + 1.f); }
;             if (nparts > 0) {
;                 for (int z = 0; z < nparts; ++z) { const f32x4* pp = (const f32x4*)(F.ws + WS_PART) + ((size_t)z * MS + (r - SP)) * (D / 4);
; #pragma unroll
;                     for (int i = 0; i < 8; ++i) xv[i] += pp[i * 64 + F.lane]; }
.LBB0_966:
	s_add_i32 s4, s2, 0xffffe000
	s_cmpk_lt_i32 s2, 0x2000
	s_cselect_b64 s[10:11], -1, 0
	s_and_b64 vcc, s[10:11], exec
	v_readlane_b32 s36, v245, 37
	s_cselect_b32 s11, s3, 0
	s_cselect_b32 s10, s2, s4
	v_readlane_b32 s38, v245, 39
	v_readlane_b32 s39, v245, 40
	s_cselect_b32 s12, s15, s39
	s_cselect_b32 s13, s14, s38
	s_lshl_b64 s[10:11], s[10:11], 13
	s_add_u32 s10, s13, s10
	s_addc_u32 s11, s12, s11
	v_lshlrev_b32_e32 v128, 4, v160
	global_load_dwordx4 v[56:59], v128, s[10:11]
	global_load_dwordx4 v[52:55], v128, s[10:11] offset:1024
	global_load_dwordx4 v[48:51], v128, s[10:11] offset:2048
	global_load_dwordx4 v[44:47], v128, s[10:11] offset:3072
	global_load_dwordx4 v[40:43], v120, s[10:11]
	global_load_dwordx4 v[36:39], v121, s[10:11]
	global_load_dwordx4 v[32:35], v122, s[10:11]
	global_load_dwordx4 v[60:63], v123, s[10:11]
	v_readlane_b32 s37, v245, 38
	v_readlane_b32 s40, v245, 41
	v_readlane_b32 s41, v245, 42
	v_readlane_b32 s42, v245, 43
	v_readlane_b32 s43, v245, 44
	v_readlane_b32 s44, v245, 45
	v_readlane_b32 s45, v245, 46
	v_readlane_b32 s46, v245, 47
	v_readlane_b32 s47, v245, 48
	v_readlane_b32 s48, v245, 49
	v_readlane_b32 s49, v245, 50
	v_readlane_b32 s50, v245, 51
	v_readlane_b32 s51, v245, 52
	s_cbranch_vccnz .LBB0_965
	s_lshr_b32 s10, s4, 2
	s_mul_hi_u32 s11, s10, 0xc000
	s_mul_i32 s10, s10, 0xc000
	v_readlane_b32 s12, v245, 54
	v_readlane_b32 s13, v245, 55
	s_add_u32 s12, s12, s10
	s_addc_u32 s13, s13, s11
	s_add_u32 s10, s12, 0x8000
	s_addc_u32 s11, s13, 0
	s_add_u32 s12, s12, 0x6000
	s_addc_u32 s13, s13, 0
	global_load_dwordx4 v[0:3], v128, s[12:13]
	global_load_dwordx4 v[4:7], v124, s[12:13]
	global_load_dwordx4 v[8:11], v125, s[12:13]
	global_load_dwordx4 v[20:23], v126, s[12:13]
	global_load_dwordx4 v[16:19], v120, s[12:13]
	global_load_dwordx4 v[24:27], v121, s[12:13]
	global_load_dwordx4 v[28:31], v122, s[12:13]
	global_load_dwordx4 v[12:15], v123, s[12:13]
	global_load_dwordx4 v[168:171], v[72:73], off
	global_load_dwordx4 v[172:175], v[72:73], off offset:1024
	global_load_dwordx4 v[176:179], v[72:73], off offset:2048
	global_load_dwordx4 v[180:183], v[72:73], off offset:3072
	global_load_dwordx4 v[184:187], v[70:71], off
	global_load_dwordx4 v[188:191], v[68:69], off
	global_load_dwordx4 v[192:195], v[66:67], off
	global_load_dwordx4 v[196:199], v[64:65], off
	global_load_dwordx4 v[200:203], v128, s[10:11]
	global_load_dwordx4 v[204:207], v124, s[10:11]
	global_load_dwordx4 v[208:211], v125, s[10:11]
	global_load_dwordx4 v[212:215], v126, s[10:11]
	global_load_dwordx4 v[216:219], v120, s[10:11]
	global_load_dwordx4 v[220:223], v121, s[10:11]
	global_load_dwordx4 v[224:227], v122, s[10:11]
	global_load_dwordx4 v[228:231], v123, s[10:11]
	s_lshl_b64 s[10:11], s[4:5], 13
	s_add_u32 s12, s16, s10
	s_addc_u32 s13, s17, s11
	s_add_u32 s20, s12, 0x400000
	s_addc_u32 s21, s13, 0
	s_waitcnt vmcnt(0)
	v_pk_add_f32 v[202:203], v[202:203], 1.0 op_sel_hi:[1,0]
	v_pk_add_f32 v[200:201], v[200:201], 1.0 op_sel_hi:[1,0]
	v_pk_mul_f32 v[76:77], v[170:171], v[202:203]
	v_pk_mul_f32 v[78:79], v[168:169], v[200:201]
	v_pk_add_f32 v[206:207], v[206:207], 1.0 op_sel_hi:[1,0]
	v_pk_add_f32 v[204:205], v[204:205], 1.0 op_sel_hi:[1,0]
	v_pk_mul_f32 v[82:83], v[174:175], v[206:207]
	v_pk_mul_f32 v[84:85], v[172:173], v[204:205]
	v_pk_add_f32 v[210:211], v[210:211], 1.0 op_sel_hi:[1,0]
	v_pk_add_f32 v[208:209], v[208:209], 1.0 op_sel_hi:[1,0]
	v_pk_mul_f32 v[86:87], v[178:179], v[210:211]
	v_pk_mul_f32 v[88:89], v[176:177], v[208:209]
	v_pk_add_f32 v[214:215], v[214:215], 1.0 op_sel_hi:[1,0]
	v_pk_add_f32 v[212:213], v[212:213], 1.0 op_sel_hi:[1,0]
	v_pk_mul_f32 v[90:91], v[182:183], v[214:215]
	v_pk_mul_f32 v[92:93], v[180:181], v[212:213]
	v_pk_add_f32 v[218:219], v[218:219], 1.0 op_sel_hi:[1,0]
	v_pk_add_f32 v[216:217], v[216:217], 1.0 op_sel_hi:[1,0]
	v_pk_mul_f32 v[94:95], v[186:187], v[218:219]
	v_pk_mul_f32 v[96:97], v[184:185], v[216:217]
	v_pk_add_f32 v[222:223], v[222:223], 1.0 op_sel_hi:[1,0]
	v_pk_add_f32 v[220:221], v[220:221], 1.0 op_sel_hi:[1,0]
	v_pk_mul_f32 v[98:99], v[190:191], v[222:223]
	v_pk_mul_f32 v[100:101], v[188:189], v[220:221]
	v_pk_add_f32 v[226:227], v[226:227], 1.0 op_sel_hi:[1,0]
	v_pk_add_f32 v[224:225], v[224:225], 1.0 op_sel_hi:[1,0]
	v_pk_mul_f32 v[102:103], v[194:195], v[226:227]
	v_pk_mul_f32 v[104:105], v[192:193], v[224:225]
	v_pk_add_f32 v[230:231], v[230:231], 1.0 op_sel_hi:[1,0]
	v_pk_add_f32 v[228:229], v[228:229], 1.0 op_sel_hi:[1,0]
	v_pk_mul_f32 v[106:107], v[198:199], v[230:231]
	v_pk_mul_f32 v[108:109], v[196:197], v[228:229]
	global_load_dwordx4 v[168:171], v128, s[12:13]
	global_load_dwordx4 v[172:175], v128, s[12:13] offset:1024
	global_load_dwordx4 v[176:179], v128, s[12:13] offset:2048
	global_load_dwordx4 v[180:183], v128, s[12:13] offset:3072
	global_load_dwordx4 v[184:187], v120, s[12:13]
	global_load_dwordx4 v[188:191], v121, s[12:13]
	global_load_dwordx4 v[192:195], v122, s[12:13]
	global_load_dwordx4 v[196:199], v123, s[12:13]
	global_load_dwordx4 v[200:203], v128, s[20:21]
	global_load_dwordx4 v[204:207], v124, s[20:21]
	global_load_dwordx4 v[208:211], v125, s[20:21]
	global_load_dwordx4 v[212:215], v126, s[20:21]
	global_load_dwordx4 v[216:219], v120, s[20:21]
	global_load_dwordx4 v[220:223], v121, s[20:21]
	global_load_dwordx4 v[224:227], v122, s[20:21]
	global_load_dwordx4 v[228:231], v123, s[20:21]
	s_add_u32 s20, s12, 0x800000
	s_addc_u32 s21, s13, 0
	s_add_u32 s12, s12, 0xc00000
	s_addc_u32 s13, s13, 0
	s_waitcnt vmcnt(8)
; template <bool GATES>
; __device__ __forceinline__ void norm_mod_phase(const Frame& F, const float* src0, const float* src1, const float* nw, int sh_off, int sc_off, int nparts, float* x1out) {
;     ...
;             if (nparts > 0) {
;                 for (int z = 0; z < nparts; ++z) { const f32x4* pp = (const f32x4*)(F.ws + WS_PART) + ((size_t)z * MS + (r - SP)) * (D / 4);
; #pragma unroll
;                     for (int i = 0; i < 8; ++i) xv[i] += pp[i * 64 + F.lane]; }
; #pragma unroll
;                 for (int i = 0; i < 8; ++i) ((f32x4*)(x1out + (size_t)(r - SP) * D))[i * 64 + F.lane] = xv[i]; } }
	v_pk_add_f32 v[58:59], v[58:59], v[170:171]
	v_pk_add_f32 v[56:57], v[56:57], v[168:169]
	v_pk_add_f32 v[54:55], v[54:55], v[174:175]
	v_pk_add_f32 v[52:53], v[52:53], v[172:173]
	v_pk_add_f32 v[50:51], v[50:51], v[178:179]
	v_pk_add_f32 v[48:49], v[48:49], v[176:177]
	v_pk_add_f32 v[46:47], v[46:47], v[182:183]
	v_pk_add_f32 v[44:45], v[44:45], v[180:181]
	v_pk_add_f32 v[42:43], v[42:43], v[186:187]
	v_pk_add_f32 v[40:41], v[40:41], v[184:185]
	v_pk_add_f32 v[38:39], v[38:39], v[190:191]
	v_pk_add_f32 v[36:37], v[36:37], v[188:189]
	v_pk_add_f32 v[34:35], v[34:35], v[194:195]
	v_pk_add_f32 v[32:33], v[32:33], v[192:193]
	v_pk_add_f32 v[62:63], v[62:63], v[198:199]
	v_pk_add_f32 v[60:61], v[60:61], v[196:197]
	global_load_dwordx4 v[168:171], v128, s[20:21]
	global_load_dwordx4 v[172:175], v124, s[20:21]
	global_load_dwordx4 v[176:179], v125, s[20:21]
	global_load_dwordx4 v[180:183], v126, s[20:21]
	global_load_dwordx4 v[184:187], v120, s[20:21]
	global_load_dwordx4 v[188:191], v121, s[20:21]
	global_load_dwordx4 v[192:195], v122, s[20:21]
	global_load_dwordx4 v[196:199], v123, s[20:21]
	s_waitcnt vmcnt(8)
	v_pk_add_f32 v[58:59], v[58:59], v[202:203]
	v_pk_add_f32 v[56:57], v[56:57], v[200:201]
	v_pk_add_f32 v[54:55], v[54:55], v[206:207]
	v_pk_add_f32 v[52:53], v[52:53], v[204:205]
	v_pk_add_f32 v[50:51], v[50:51], v[210:211]
	v_pk_add_f32 v[48:49], v[48:49], v[208:209]
	v_pk_add_f32 v[46:47], v[46:47], v[214:215]
	v_pk_add_f32 v[44:45], v[44:45], v[212:213]
	v_pk_add_f32 v[42:43], v[42:43], v[218:219]
	v_pk_add_f32 v[40:41], v[40:41], v[216:217]
	v_pk_add_f32 v[38:39], v[38:39], v[222:223]
	v_pk_add_f32 v[36:37], v[36:37], v[220:221]
	v_pk_add_f32 v[34:35], v[34:35], v[226:227]
	v_pk_add_f32 v[32:33], v[32:33], v[224:225]
	v_pk_add_f32 v[62:63], v[62:63], v[230:231]
	v_pk_add_f32 v[60:61], v[60:61], v[228:229]
	global_load_dwordx4 v[200:203], v128, s[12:13]
	global_load_dwordx4 v[204:207], v124, s[12:13]
	global_load_dwordx4 v[208:211], v125, s[12:13]
	global_load_dwordx4 v[212:215], v126, s[12:13]
	global_load_dwordx4 v[216:219], v120, s[12:13]
	global_load_dwordx4 v[220:223], v121, s[12:13]
	global_load_dwordx4 v[224:227], v122, s[12:13]
	global_load_dwordx4 v[228:231], v123, s[12:13]
	s_waitcnt vmcnt(8)
	v_pk_add_f32 v[58:59], v[58:59], v[170:171]
	v_pk_add_f32 v[56:57], v[56:57], v[168:169]
	v_pk_add_f32 v[54:55], v[54:55], v[174:175]
	v_pk_add_f32 v[52:53], v[52:53], v[172:173]
	v_pk_add_f32 v[50:51], v[50:51], v[178:179]
	v_pk_add_f32 v[48:49], v[48:49], v[176:177]
	v_pk_add_f32 v[46:47], v[46:47], v[182:183]
	v_pk_add_f32 v[44:45], v[44:45], v[180:181]
	v_pk_add_f32 v[42:43], v[42:43], v[186:187]
	v_pk_add_f32 v[40:41], v[40:41], v[184:185]
	v_pk_add_f32 v[38:39], v[38:39], v[190:191]
	v_pk_add_f32 v[36:37], v[36:37], v[188:189]
	v_pk_add_f32 v[34:35], v[34:35], v[194:195]
	v_pk_add_f32 v[32:33], v[32:33], v[192:193]
	v_pk_add_f32 v[62:63], v[62:63], v[198:199]
	v_pk_add_f32 v[60:61], v[60:61], v[196:197]
	s_waitcnt vmcnt(0)
	v_pk_add_f32 v[58:59], v[58:59], v[202:203]
	v_pk_add_f32 v[56:57], v[56:57], v[200:201]
	v_pk_add_f32 v[54:55], v[54:55], v[206:207]
	v_pk_add_f32 v[52:53], v[52:53], v[204:205]
	v_pk_add_f32 v[50:51], v[50:51], v[210:211]
	v_pk_add_f32 v[48:49], v[48:49], v[208:209]
	v_pk_add_f32 v[46:47], v[46:47], v[214:215]
	v_pk_add_f32 v[44:45], v[44:45], v[212:213]
	v_pk_add_f32 v[42:43], v[42:43], v[218:219]
	v_pk_add_f32 v[40:41], v[40:41], v[216:217]
	v_pk_add_f32 v[38:39], v[38:39], v[222:223]
	v_pk_add_f32 v[36:37], v[36:37], v[220:221]
	v_pk_add_f32 v[34:35], v[34:35], v[226:227]
	v_pk_add_f32 v[32:33], v[32:33], v[224:225]
	v_pk_add_f32 v[62:63], v[62:63], v[230:231]
	v_pk_add_f32 v[60:61], v[60:61], v[228:229]
	v_lshl_add_u64 v[110:111], v[74:75], 0, s[10:11]
	global_store_dwordx4 v[110:111], v[56:59], off
	global_store_dwordx4 v[110:111], v[52:55], off offset:1024
	global_store_dwordx4 v[110:111], v[48:51], off offset:2048
	global_store_dwordx4 v[110:111], v[44:47], off offset:3072
	v_add_co_u32_e32 v110, vcc, s18, v110
	s_nop 1
	v_addc_co_u32_e32 v111, vcc, 0, v111, vcc
	global_store_dwordx4 v[110:111], v[40:43], off
	global_store_dwordx4 v[110:111], v[36:39], off offset:1024
	global_store_dwordx4 v[110:111], v[32:35], off offset:2048
	global_store_dwordx4 v[110:111], v[60:63], off offset:3072
	s_branch .LBB0_965
